# v11: FoX unit: next queue entry fetched at unit start, gate rows loaded ahead of O staging, K/V DMA before forget-gate image; BATT rel-bias table in LDS + counted K wait; GEMM deferred epilogue + fast
# baseline (speedup 1.0000x reference)
.LBB0_82:
	s_mov_b32 s1, 0x8000
	v_add_co_u32_e32 v2, vcc, s1, v0
	s_mov_b32 s1, 0xa000
	s_nop 0
	v_addc_co_u32_e32 v3, vcc, 0, v1, vcc
	v_add_co_u32_e32 v4, vcc, s1, v0
	s_mov_b32 s1, 0xc000
	s_nop 0
	v_addc_co_u32_e32 v5, vcc, 0, v1, vcc
	global_load_dwordx4 v[96:99], v[2:3], off
	global_load_dwordx4 v[102:105], v[4:5], off
	v_add_co_u32_e32 v2, vcc, s1, v0
	s_mov_b32 s1, 0xe000
	s_nop 0
	v_addc_co_u32_e32 v3, vcc, 0, v1, vcc
	v_add_co_u32_e32 v4, vcc, s1, v0
	s_mov_b32 s1, 0x10000
	s_nop 0
	v_addc_co_u32_e32 v5, vcc, 0, v1, vcc
	global_load_dwordx4 v[106:109], v[2:3], off
	global_load_dwordx4 v[110:113], v[4:5], off
	v_add_co_u32_e32 v2, vcc, s1, v0
	s_mov_b32 s1, 0x12000
	s_nop 0
	v_addc_co_u32_e32 v3, vcc, 0, v1, vcc
	v_add_co_u32_e32 v4, vcc, s1, v0
	s_mov_b32 s1, 0x14000
	s_nop 0
	v_addc_co_u32_e32 v5, vcc, 0, v1, vcc
	global_load_dwordx4 v[114:117], v[2:3], off
	global_load_dwordx4 v[118:121], v[4:5], off
	v_add_co_u32_e32 v2, vcc, s1, v0
	s_mov_b32 s1, 0x16000
	s_nop 0
	v_addc_co_u32_e32 v3, vcc, 0, v1, vcc
	v_add_co_u32_e32 v0, vcc, s1, v0
	s_mul_i32 s1, s21, 0xc0000
	s_nop 0
	v_addc_co_u32_e32 v1, vcc, 0, v1, vcc
	global_load_dwordx4 v[122:125], v[2:3], off
	global_load_dwordx4 v[126:129], v[0:1], off
	s_mul_hi_u32 s6, s20, 0xc0000
	s_add_i32 s6, s6, s1
	s_add_u32 s64, s44, 0x3b800000
	v_readlane_b32 s28, v242, 63
	s_addc_u32 s65, s45, 0
	s_lshl_b32 s7, s28, 7
	s_add_i32 s78, s7, 0
	s_lshl_b32 s7, s28, 12
	s_add_i32 s79, s7, 0
	s_mul_i32 s1, s20, 0xc0000
	s_lshl_b32 s69, s28, 5
	s_add_i32 s78, s78, 0x18400
	s_add_i32 s79, s79, 0x18800
	v_readlane_b32 s20, v242, 45
	v_readlane_b32 s21, v242, 46
	s_add_u32 s7, s12, s20
	s_addc_u32 s12, s13, s21
	v_readlane_b32 s13, v242, 47
	s_add_u32 s50, s7, s13
	s_addc_u32 s51, s12, 0
	s_add_u32 s42, s64, s1
	s_addc_u32 s43, s65, s6
	s_lshl_b32 s1, s28, 13
	s_cmp_lt_i32 s28, 4
	s_cselect_b64 s[12:13], -1, 0
	s_cmp_lt_i32 s28, 3
	s_cselect_b64 s[20:21], -1, 0
	s_cmp_lt_i32 s28, 2
	s_cselect_b64 s[22:23], -1, 0
	s_cmp_lt_i32 s28, 1
	s_cselect_b64 s[24:25], -1, 0
	s_cmp_lt_i32 s28, 0
	s_cselect_b64 s[40:41], -1, 0
	s_add_i32 s80, s1, 0
	v_readlane_b32 s1, v242, 21
	s_mov_b32 s66, s1
	v_readlane_b32 s81, v242, 37
	v_readlane_b32 s67, v242, 34
	v_readlane_b32 s84, v242, 20
	v_readlane_b32 s89, v243, 63
	s_waitcnt lgkmcnt(0)
	v_lshlrev_b32_e32 v244, 2, v225
	global_load_dword v245, v244, s[2:3]
	v_and_b32_e32 v246, 0xff, v225
	v_lshlrev_b32_e32 v246, 2, v246
	global_load_dword v247, v246, s[2:3] offset:2048
	s_waitcnt vmcnt(0)
	v_add_u32_e32 v244, 0x21000, v244
	ds_write_b32 v244, v245
	v_add_u32_e32 v246, 0x21800, v246
	ds_write_b32 v246, v247
	s_waitcnt lgkmcnt(0)
	s_barrier
	s_mov_b32 s100, 0
	s_branch .LBB0_84
.LBB0_83:
	s_mov_b32 s100, 1
	s_or_b64 exec, exec, s[28:29]
	s_and_b64 vcc, exec, s[70:71]
	s_mov_b32 s66, s54
	s_mov_b32 s67, s47
	s_mov_b32 s84, s52
	s_mov_b64 s[42:43], s[72:73]
	s_mov_b64 s[50:51], s[6:7]
	s_mov_b32 s89, s34
	s_waitcnt lgkmcnt(0)
	s_barrier
	s_cbranch_vccnz .LBB0_134

.LBB0_88:
	s_or_b64 exec, exec, s[30:31]
	v_mov_b32_e32 v8, s66
	v_mad_u64_u32 v[4:5], s[30:31], v4, 24, v[8:9]
	v_ashrrev_i32_e32 v5, 31, v4
	s_waitcnt lgkmcnt(0)
	v_lshlrev_b32_e32 v4, 2, v4
	v_add_u32_e32 v4, 0x21000, v4
	ds_read_b32 v4, v4
	s_waitcnt lgkmcnt(0)
	v_mul_f32_e32 v4, 0x3fb8aa3b, v4

.LBB0_90:
	s_or_b64 exec, exec, s[6:7]
	v_ashrrev_i32_e32 v4, 4, v6
	v_lshlrev_b32_e32 v5, 2, v4
	v_and_b32_e32 v7, 15, v6
	v_and_b32_e32 v5, 12, v5
	v_bfe_u32 v8, v4, 2, 2
	v_bitop3_b32 v5, v5, v7, v8 bitop3:0x36
	v_lshlrev_b32_e32 v5, 4, v5
	v_lshlrev_b32_e32 v8, 8, v4
	v_add3_u32 v211, 0, v5, v8
	v_cvt_f32_u32_e32 v5, s84
	s_sub_i32 s1, 0, s84
	v_mov_b32_e32 v8, s67
	v_lshlrev_b32_e32 v100, 4, v7
	v_rcp_iflag_f32_e32 v5, v5
	v_and_b32_e32 v213, 63, v6
	v_add_u32_e32 v228, 0x10000, v211
	v_add_u32_e32 v229, 0x12000, v211
	v_mul_f32_e32 v5, 0x4f7ffffe, v5
	v_cvt_u32_f32_e32 v5, v5
	v_add_u32_e32 v230, 0x14000, v211
	v_add_u32_e32 v231, 0x16000, v211
	s_cmp_eq_u32 s100, 0
	s_cbranch_scc1 .Lmy_batt_first
	s_waitcnt vmcnt(16)
	s_branch .Lmy_batt_join

.Lmy_batt_join:
	ds_write_b128 v211, v[80:83]
	ds_write_b128 v211, v[84:87] offset:8192
	ds_write_b128 v211, v[88:91] offset:16384
	ds_write_b128 v211, v[92:95] offset:24576
	ds_write_b128 v211, v[96:99] offset:32768
	ds_write_b128 v211, v[102:105] offset:40960
	ds_write_b128 v211, v[106:109] offset:49152
	ds_write_b128 v211, v[110:113] offset:57344
	v_readfirstlane_b32 s6, v5
	s_mul_i32 s1, s1, s6
	s_mul_hi_u32 s1, s6, s1
	s_add_i32 s6, s6, s1
	s_lshr_b32 s1, s6, 19
	s_mul_i32 s6, s1, s84
	s_sub_i32 s6, 0x2000, s6
	s_add_i32 s7, s1, 1
	s_sub_i32 s28, s6, s84
	s_cmp_ge_u32 s6, s84
	s_cselect_b32 s1, s7, s1
	s_cselect_b32 s6, s28, s6
	s_add_i32 s7, s1, 1
	s_cmp_ge_u32 s6, s84
	s_cselect_b32 s1, s7, s1
	s_add_u32 s6, s34, 0xffffff80
	v_ashrrev_i32_e32 v5, 31, v4
	s_addc_u32 s7, 0, 0xffffff
	v_lshl_add_u64 v[4:5], s[6:7], 0, v[4:5]
	v_mad_u64_u32 v[4:5], s[6:7], s1, v8, v[4:5]
	v_lshlrev_b64 v[4:5], 8, v[4:5]
	v_lshl_add_u64 v[4:5], s[4:5], 0, v[4:5]
	s_cmp_gt_i32 s81, 0
	v_lshl_add_u64 v[4:5], v[4:5], 0, v[100:101]
	s_mov_b64 s[6:7], 0x1000000
	s_cselect_b64 s[28:29], -1, 0
	s_cmp_lt_i32 s81, 1
	v_lshl_add_u64 v[4:5], v[4:5], 0, s[6:7]
	ds_write_b128 v228, v[114:117]
	ds_write_b128 v229, v[118:121]
	ds_write_b128 v230, v[122:125]
	ds_write_b128 v231, v[126:129]
	s_waitcnt lgkmcnt(0)
	s_barrier
	s_cbranch_scc1 .LBB0_92
	global_load_dwordx4 v[130:133], v[4:5], off
	s_branch .LBB0_93

.LBB0_276:
	v_mov_b32_e32 v0, s0
	s_waitcnt lgkmcnt(0)
	s_barrier
	ds_read_b32 v0, v0
	s_add_i32 s52, s10, 0x100
	s_ashr_i32 s47, s52, 6
	v_add_u32_e32 v19, 0x200, v181
	v_add_u32_e32 v18, 0x400, v181
	s_waitcnt lgkmcnt(0)
	v_readfirstlane_b32 s1, v0
	s_lshl_b32 s84, s1, 7
	s_lshl_b32 s50, s1, 1
	v_writelane_b32 v241, s16, 30
	v_writelane_b32 v241, s17, 31
	v_writelane_b32 v241, s18, 32
	v_writelane_b32 v241, s19, 33
	v_writelane_b32 v241, s20, 34
	v_writelane_b32 v241, s21, 35
	s_lshl_b64 s[16:17], s[30:31], 24
	s_add_u32 s18, s14, s16
	s_addc_u32 s19, s15, s17
	s_add_u32 s18, s18, s92
	s_addc_u32 s19, s19, s93
	s_add_u32 s20, s71, s16
	s_addc_u32 s21, s72, s17
	s_add_u32 s20, s20, s92
	s_addc_u32 s21, s21, s93
	s_mov_b32 s100, s50
	s_ashr_i32 s101, s50, 31
	s_lshl_b64 s[16:17], s[100:101], 17
	s_add_u32 s18, s18, s16
	s_addc_u32 s19, s19, s17
	s_add_u32 s20, s20, s16
	s_addc_u32 s21, s21, s17
	s_lshl_b32 s100, s69, 4
	v_lshl_add_u32 v198, v178, 11, s100
	v_lshrrev_b32_e32 v199, 2, v178
	v_and_or_b32 v199, s100, 48, v199
	s_ashr_i32 s101, s34, 8
	s_lshl_b32 s101, s101, 5
	v_lshl_add_u32 v199, v199, 10, s101
	v_lshlrev_b32_e32 v200, 3, v32
	v_and_b32_e32 v200, 24, v200
	v_or_b32_e32 v199, v199, v200
	v_lshlrev_b32_e32 v199, 1, v199
	s_lshl_b32 s100, s69, 10
	s_mov_b32 s101, m0
	s_mov_b32 m0, s100
	s_nop 0
	global_load_lds_dwordx4 v198, s[18:19]
	s_add_i32 m0, s100, 0x6000
	s_nop 0
	global_load_lds_dwordx4 v199, s[20:21]
	s_add_u32 s16, s18, 0x20000
	s_addc_u32 s17, s19, 0
	s_add_i32 m0, s100, 0x2000
	s_nop 0
	global_load_lds_dwordx4 v198, s[16:17]
	s_add_u32 s16, s18, 0x40000
	s_addc_u32 s17, s19, 0
	s_add_i32 m0, s100, 0x4000
	s_nop 0
	global_load_lds_dwordx4 v198, s[16:17]
	s_mov_b32 m0, s101
	v_mov_b32_e32 v201, 0
	v_cmp_eq_u32_e32 vcc, 0, v181
	s_and_saveexec_b64 s[16:17], vcc
	s_cbranch_execz .Lmy_fox_noq
	v_mov_b32_e32 v201, 1
	global_atomic_add v201, v101, v201, s[58:59] sc0
.Lmy_fox_noq:
	s_or_b64 exec, exec, s[16:17]
	v_readlane_b32 s16, v241, 30
	v_readlane_b32 s17, v241, 31
	v_readlane_b32 s18, v241, 32
	v_readlane_b32 s19, v241, 33
	v_readlane_b32 s20, v241, 34
	v_readlane_b32 s21, v241, 35
	s_ashr_i32 s85, s84, 31
	s_sub_i32 s78, s47, s50
	s_lshl_b64 s[6:7], s[84:85], 2
	s_add_u32 s10, s39, s6
	s_addc_u32 s11, s54, s7
	s_lshl_b32 s33, s78, 4
	v_cmp_gt_i32_e64 s[8:9], s33, v19
	v_cmp_gt_i32_e64 s[6:7], s33, v18
	v_add_u32_e32 v17, 0x600, v181
	v_cndmask_b32_e64 v2, v181, v19, s[8:9]
	v_lshlrev_b32_e32 v2, 2, v2
	v_ashrrev_i32_e32 v3, 31, v2
	v_lshl_add_u64 v[8:9], v[2:3], 2, s[10:11]
	v_cndmask_b32_e64 v2, v181, v18, s[6:7]
	v_lshlrev_b32_e32 v2, 2, v2
	v_ashrrev_i32_e32 v3, 31, v2
	v_cmp_gt_i32_e32 vcc, s33, v17
	v_lshl_add_u64 v[4:5], v[2:3], 2, s[10:11]
	v_lshlrev_b32_e32 v0, 2, v181
	v_cndmask_b32_e32 v2, v181, v17, vcc
	v_lshlrev_b32_e32 v2, 2, v2
	v_ashrrev_i32_e32 v1, 31, v0
	v_ashrrev_i32_e32 v3, 31, v2
	v_lshl_add_u64 v[0:1], v[0:1], 2, s[10:11]
	v_lshl_add_u64 v[2:3], v[2:3], 2, s[10:11]
	global_load_dwordx4 v[12:15], v[0:1], off
	s_nop 0
	global_load_dwordx4 v[0:3], v[2:3], off
	s_nop 0
	global_load_dwordx4 v[4:7], v[4:5], off
	s_nop 0
	global_load_dwordx4 v[8:11], v[8:9], off
	s_lshl_b32 s1, s1, 2
	s_add_i32 s29, s1, 0
	v_lshlrev_b32_e32 v33, 4, v181
	s_add_i32 s29, s29, 0x1c800
	v_cmp_gt_i32_e64 s[10:11], s33, v181
	s_waitcnt vmcnt(0)
	s_and_saveexec_b64 s[60:61], s[10:11]
	s_cbranch_execz .LBB0_280
	v_ashrrev_i32_e32 v20, 5, v181
	v_lshl_add_u32 v20, v20, 2, s29
	ds_read_b32 v20, v20
	s_waitcnt lgkmcnt(0)
	v_add_f32_e32 v12, v12, v20
	v_mul_f32_e32 v12, 0xbfb8aa3b, v12
	v_cvt_pk_bf16_f32 v21, v12, 0
	v_lshlrev_b32_e32 v21, 16, v21
	v_add_f32_e32 v13, v13, v20
	v_sub_f32_e32 v21, v12, v21
	v_mul_f32_e32 v13, 0xbfb8aa3b, v13
	v_add_f32_e32 v15, v15, v20
	v_cvt_pk_bf16_f32 v12, v12, v21
	v_cvt_pk_bf16_f32 v21, v13, 0
	v_mul_f32_e32 v15, 0xbfb8aa3b, v15
	v_lshlrev_b32_e32 v21, 16, v21
	v_add_f32_e32 v14, v14, v20
	v_cvt_pk_bf16_f32 v20, v15, 0
	v_sub_f32_e32 v21, v13, v21
	v_mul_f32_e32 v14, 0xbfb8aa3b, v14
	v_lshlrev_b32_e32 v20, 16, v20
	v_cvt_pk_bf16_f32 v13, v13, v21
	v_cvt_pk_bf16_f32 v21, v14, 0
	v_sub_f32_e32 v20, v15, v20
	v_lshlrev_b32_e32 v21, 16, v21
	v_cvt_pk_bf16_f32 v15, v15, v20
	v_add_u32_e32 v20, 0, v33
	v_sub_f32_e32 v21, v14, v21
	v_add_u32_e32 v20, 0x14800, v20
	v_cvt_pk_bf16_f32 v14, v14, v21
	ds_write_b128 v20, v[12:15]
	s_or_b64 exec, exec, s[60:61]
	s_and_saveexec_b64 s[10:11], s[8:9]
	s_cbranch_execnz .LBB0_281

.LBB0_307:
	s_cmp_lg_u32 0, -1
	s_cselect_b32 s1, 0, 0
	s_addk_i32 s1, 0x6000
	v_add3_u32 v64, v185, s1, v183
	v_cvt_pk_bf16_f32 v68, v48, v49
	v_cvt_pk_bf16_f32 v69, v50, v51
	v_cvt_pk_bf16_f32 v70, v52, v53
	v_cvt_pk_bf16_f32 v71, v54, v55
	v_cvt_pk_bf16_f32 v72, v56, v57
	v_cvt_pk_bf16_f32 v73, v58, v59
	v_cvt_pk_bf16_f32 v74, v60, v61
	v_cvt_pk_bf16_f32 v75, v62, v63
	v_cvt_pk_bf16_f32 v76, v32, v33
	v_cvt_pk_bf16_f32 v77, v34, v35
	v_cvt_pk_bf16_f32 v78, v36, v37
	v_cvt_pk_bf16_f32 v79, v38, v39
	v_cvt_pk_bf16_f32 v80, v40, v41
	v_cvt_pk_bf16_f32 v81, v42, v43
	v_cvt_pk_bf16_f32 v82, v44, v45
	v_cvt_pk_bf16_f32 v83, v46, v47
	v_add3_u32 v64, v64, v186, s34
	ds_read_b64_tr_b16 v[84:85],v64 offset:0
	ds_read_b64_tr_b16 v[86:87],v64 offset:512
	ds_read_b64_tr_b16 v[88:89],v64 offset:1024
	ds_read_b64_tr_b16 v[90:91],v64 offset:1536
	ds_read_b64_tr_b16 v[92:93],v64 offset:2048
	ds_read_b64_tr_b16 v[94:95],v64 offset:2560
	ds_read_b64_tr_b16 v[96:97],v64 offset:3072
	ds_read_b64_tr_b16 v[98:99],v64 offset:3584
	s_waitcnt lgkmcnt(0)
	s_nop 0
	v_mfma_f32_32x32x16_bf16 v[0:15], v[68:71], v[84:87], v[0:15]
	ds_read_b64_tr_b16 v[84:85],v64 offset:4096
	ds_read_b64_tr_b16 v[86:87],v64 offset:4608
	v_mfma_f32_32x32x16_bf16 v[0:15], v[72:75], v[88:91], v[0:15]
	ds_read_b64_tr_b16 v[88:89],v64 offset:5120
	ds_read_b64_tr_b16 v[90:91],v64 offset:5632
	v_mfma_f32_32x32x16_bf16 v[0:15], v[76:79], v[92:95], v[0:15]
	ds_read_b64_tr_b16 v[92:93],v64 offset:6144
	ds_read_b64_tr_b16 v[94:95],v64 offset:6656
	v_mfma_f32_32x32x16_bf16 v[0:15], v[80:83], v[96:99], v[0:15]
	ds_read_b64_tr_b16 v[96:97],v64 offset:7168
	ds_read_b64_tr_b16 v[98:99],v64 offset:7680
	s_waitcnt lgkmcnt(0)
	v_mfma_f32_32x32x16_bf16 v[16:31], v[68:71], v[84:87], v[16:31]
	v_cmp_eq_u32_e32 vcc, 0, v181
	v_mov_b32_e32 v64, 0
	v_mfma_f32_32x32x16_bf16 v[16:31], v[72:75], v[88:91], v[16:31]
	v_mfma_f32_32x32x16_bf16 v[16:31], v[76:79], v[92:95], v[16:31]
	v_mfma_f32_32x32x16_bf16 v[16:31], v[80:83], v[96:99], v[16:31]
	v_mov_b32_e32 v64, v201
	s_add_u32 s100, s12, s92
	s_addc_u32 s101, s13, s93
	v_ashrrev_i32_e32 v244, 3, v178
	v_mov_b32_e32 v245, 0
	v_lshl_add_u64 v[244:245], s[42:43], 0, v[244:245]
	v_lshlrev_b64 v[244:245], 11, v[244:245]
	v_lshlrev_b32_e32 v246, 4, v178
	v_and_b32_e32 v246, 0x70, v246
	v_mov_b32_e32 v247, 0
	v_lshl_add_u64 v[246:247], s[100:101], 0, v[246:247]
	v_lshl_add_u64 v[244:245], v[246:247], 0, v[244:245]
	s_mov_b32 s100, 0x4000
	s_mov_b32 s101, 0
	global_load_dwordx4 v[208:211], v[244:245], off
	v_lshl_add_u64 v[244:245], v[244:245], 0, s[100:101]
	global_load_dwordx4 v[226:229], v[244:245], off
	v_lshl_add_u64 v[244:245], v[244:245], 0, s[100:101]
	global_load_dwordx4 v[230:233], v[244:245], off
	v_lshl_add_u64 v[244:245], v[244:245], 0, s[100:101]
	global_load_dwordx4 v[234:237], v[244:245], off
	v_add_f32_e32 v48, v48, v49
	v_add_f32_e32 v48, v50, v48
	v_add_f32_e32 v48, v51, v48
	v_add_f32_e32 v48, v52, v48
	v_add_f32_e32 v48, v53, v48
	v_add_f32_e32 v48, v54, v48
	v_add_f32_e32 v48, v55, v48
	v_add_f32_e32 v48, v56, v48
	v_add_f32_e32 v48, v57, v48
	v_add_f32_e32 v48, v58, v48
	v_add_f32_e32 v48, v59, v48
	v_add_f32_e32 v48, v60, v48
	v_add_f32_e32 v48, v61, v48
	v_add_f32_e32 v48, v62, v48
	v_add_f32_e32 v48, v63, v48
	v_add_f32_e32 v32, v32, v48
	v_add_f32_e32 v32, v33, v32
	v_add_f32_e32 v32, v34, v32
	v_add_f32_e32 v32, v35, v32
	v_add_f32_e32 v32, v36, v32
	v_add_f32_e32 v32, v37, v32
	v_add_f32_e32 v32, v38, v32
	v_add_f32_e32 v32, v39, v32
	v_add_f32_e32 v32, v40, v32
	v_add_f32_e32 v32, v41, v32
	v_add_f32_e32 v32, v42, v32
	v_add_f32_e32 v32, v43, v32
	v_add_f32_e32 v32, v44, v32
	v_add_f32_e32 v32, v45, v32
	v_add_f32_e32 v32, v46, v32
	v_add_f32_e32 v32, v47, v32
	v_add_f32_e32 v32, v65, v32
	v_mov_b32_e32 v33, v32
	s_nop 1
	v_permlane32_swap_b32_e32 v32, v33
	s_and_saveexec_b64 s[8:9], s[6:7]
	v_lshl_add_u32 v34, v179, 2, s41
	v_add_f32_e32 v32, v32, v33
	ds_write_b32 v34, v32 offset:49280
	s_or_b64 exec, exec, s[8:9]
	s_waitcnt lgkmcnt(0)
	ds_read_b128 v[32:35], v66 offset:49280
	ds_read_b128 v[36:39], v66 offset:49312
	s_lshl_b64 s[6:7], s[10:11], 1
	s_add_u32 s1, s73, s6
	s_addc_u32 s7, s64, s7
	s_waitcnt lgkmcnt(1)
	v_rcp_f32_e32 v40, v32
	s_lshl_b32 s6, s69, 12
	v_rcp_f32_e32 v41, v33
	s_add_i32 s8, s6, 0
	v_lshlrev_b32_e32 v48, 1, v179
	v_lshlrev_b32_e32 v49, 9, v180
	v_mul_f32_e32 v0, v0, v40
	v_add3_u32 v48, s8, v48, v49
	v_cvt_pk_bf16_f32 v0, v0, s0
	v_rcp_f32_e32 v42, v34
	v_rcp_f32_e32 v43, v35
	s_waitcnt lgkmcnt(0)
	v_rcp_f32_e32 v44, v36
	ds_read_b128 v[32:35], v66 offset:49344
	v_rcp_f32_e32 v45, v37
	v_rcp_f32_e32 v46, v38
	v_rcp_f32_e32 v47, v39
	ds_read_b128 v[36:39], v66 offset:49376
	ds_write_b16 v48, v0 offset:51200
	v_mul_f32_e32 v0, v16, v40
	v_cvt_pk_bf16_f32 v0, v0, s0
	ds_write_b16 v48, v0 offset:51264
	v_mul_f32_e32 v0, v1, v41
	v_cvt_pk_bf16_f32 v0, v0, s0
	ds_write_b16 v48, v0 offset:51328
	v_mul_f32_e32 v0, v17, v41
	v_cvt_pk_bf16_f32 v0, v0, s0
	ds_write_b16 v48, v0 offset:51392
	v_mul_f32_e32 v0, v2, v42
	v_cvt_pk_bf16_f32 v0, v0, s0
	ds_write_b16 v48, v0 offset:51456
	v_mul_f32_e32 v0, v18, v42
	v_cvt_pk_bf16_f32 v0, v0, s0
	ds_write_b16 v48, v0 offset:51520
	v_mul_f32_e32 v0, v3, v43
	v_cvt_pk_bf16_f32 v0, v0, s0
	ds_write_b16 v48, v0 offset:51584
	v_mul_f32_e32 v0, v19, v43
	v_cvt_pk_bf16_f32 v0, v0, s0
	ds_write_b16 v48, v0 offset:51648
	v_mul_f32_e32 v0, v4, v44
	v_cvt_pk_bf16_f32 v0, v0, s0
	ds_write_b16 v48, v0 offset:52224
	v_mul_f32_e32 v0, v20, v44
	v_cvt_pk_bf16_f32 v0, v0, s0
	ds_write_b16 v48, v0 offset:52288
	v_mul_f32_e32 v0, v5, v45
	v_cvt_pk_bf16_f32 v0, v0, s0
	ds_write_b16 v48, v0 offset:52352
	v_mul_f32_e32 v0, v21, v45
	v_cvt_pk_bf16_f32 v0, v0, s0
	ds_write_b16 v48, v0 offset:52416
	v_mul_f32_e32 v0, v6, v46
	v_cvt_pk_bf16_f32 v0, v0, s0
	ds_write_b16 v48, v0 offset:52480
	v_mul_f32_e32 v0, v22, v46
	v_cvt_pk_bf16_f32 v0, v0, s0
	s_waitcnt lgkmcnt(14)
	v_rcp_f32_e32 v32, v32
	ds_write_b16 v48, v0 offset:52544
	v_mul_f32_e32 v0, v7, v47
	v_cvt_pk_bf16_f32 v0, v0, s0
	ds_write_b16 v48, v0 offset:52608
	v_mul_f32_e32 v0, v23, v47
	v_cvt_pk_bf16_f32 v0, v0, s0
	v_rcp_f32_e32 v33, v33
	ds_write_b16 v48, v0 offset:52672
	v_mul_f32_e32 v0, v8, v32
	v_cvt_pk_bf16_f32 v0, v0, s0
	ds_write_b16 v48, v0 offset:53248
	v_mul_f32_e32 v0, v24, v32
	v_cvt_pk_bf16_f32 v0, v0, s0
	v_rcp_f32_e32 v34, v34
	ds_write_b16 v48, v0 offset:53312
	v_mul_f32_e32 v0, v9, v33
	v_cvt_pk_bf16_f32 v0, v0, s0
	ds_write_b16 v48, v0 offset:53376
	v_mul_f32_e32 v0, v25, v33
	v_cvt_pk_bf16_f32 v0, v0, s0
	v_rcp_f32_e32 v35, v35
	ds_write_b16 v48, v0 offset:53440
	v_mul_f32_e32 v0, v10, v34
	v_cvt_pk_bf16_f32 v0, v0, s0
	ds_write_b16 v48, v0 offset:53504
	v_mul_f32_e32 v0, v26, v34
	v_cvt_pk_bf16_f32 v0, v0, s0
	s_waitcnt lgkmcnt(14)
	v_rcp_f32_e32 v36, v36
	ds_write_b16 v48, v0 offset:53568
	v_mul_f32_e32 v0, v11, v35
	v_cvt_pk_bf16_f32 v0, v0, s0
	ds_write_b16 v48, v0 offset:53632
	v_mul_f32_e32 v0, v27, v35
	v_cvt_pk_bf16_f32 v0, v0, s0
	v_rcp_f32_e32 v37, v37
	ds_write_b16 v48, v0 offset:53696
	v_mul_f32_e32 v0, v12, v36
	v_cvt_pk_bf16_f32 v0, v0, s0
	ds_write_b16 v48, v0 offset:54272
	v_mul_f32_e32 v0, v28, v36
	v_cvt_pk_bf16_f32 v0, v0, s0
	v_rcp_f32_e32 v38, v38
	ds_write_b16 v48, v0 offset:54336
	v_mul_f32_e32 v0, v13, v37
	v_cvt_pk_bf16_f32 v0, v0, s0
	ds_write_b16 v48, v0 offset:54400
	v_mul_f32_e32 v0, v29, v37
	v_cvt_pk_bf16_f32 v0, v0, s0
	v_rcp_f32_e32 v39, v39
	ds_write_b16 v48, v0 offset:54464
	v_mul_f32_e32 v0, v14, v38
	v_cvt_pk_bf16_f32 v0, v0, s0
	ds_write_b16 v48, v0 offset:54528
	v_mul_f32_e32 v0, v30, v38
	v_cvt_pk_bf16_f32 v0, v0, s0
	ds_write_b16 v48, v0 offset:54592
	v_mul_f32_e32 v0, v15, v39
	v_cvt_pk_bf16_f32 v0, v0, s0
	ds_write_b16 v48, v0 offset:54656
	v_mul_f32_e32 v0, v31, v39
	v_cvt_pk_bf16_f32 v0, v0, s0
	ds_write_b16 v48, v0 offset:54720
	s_add_u32 s6, s1, s92
	s_addc_u32 s7, s7, s93
	s_waitcnt lgkmcnt(0)
	s_add_u32 s10, s12, s92
	v_ashrrev_i32_e32 v2, 3, v178
	v_lshlrev_b32_e32 v0, 4, v178
	v_ashrrev_i32_e32 v3, 31, v2
	v_and_b32_e32 v100, 0x70, v0
	s_addc_u32 s11, s13, s93
	v_lshl_add_u64 v[0:1], s[42:43], 0, v[2:3]
	v_lshl_add_u64 v[4:5], s[10:11], 0, v[100:101]
	v_lshlrev_b64 v[0:1], 11, v[0:1]
	v_lshl_add_u64 v[0:1], v[4:5], 0, v[0:1]
	s_waitcnt vmcnt(0)
	v_mov_b32_e32 v8, v208
	v_mov_b32_e32 v9, v209
	v_mov_b32_e32 v10, v210
	v_mov_b32_e32 v11, v211
	v_add_u32_e32 v6, 8, v2
	v_ashrrev_i32_e32 v7, 31, v6
	v_lshl_add_u64 v[0:1], s[42:43], 0, v[6:7]
	v_lshlrev_b64 v[0:1], 11, v[0:1]
	v_lshl_add_u64 v[0:1], v[4:5], 0, v[0:1]
	v_mov_b32_e32 v12, v226
	v_mov_b32_e32 v13, v227
	v_mov_b32_e32 v14, v228
	v_mov_b32_e32 v15, v229
	v_add_u32_e32 v32, s8, v100
	v_lshl_add_u32 v0, v2, 7, v32
	ds_read_b128 v[16:19], v0 offset:51200
	s_waitcnt lgkmcnt(0)
	v_lshlrev_b32_e32 v24, 16, v16
	v_and_b32_e32 v25, 0xffff0000, v16
	s_waitcnt vmcnt(1)
	v_lshlrev_b32_e32 v20, 16, v8
	v_and_b32_e32 v21, 0xffff0000, v8
	v_mul_f32_e32 v1, 0xbfb8aa3b, v20
	v_exp_f32_e32 v1, v1
	v_mul_f32_e32 v8, 0xbfb8aa3b, v21
	v_exp_f32_e32 v8, v8
	s_waitcnt vmcnt(0)
	v_lshlrev_b32_e32 v28, 16, v12
	v_add_f32_e32 v0, 1.0, v1
	v_rcp_f32_e32 v22, v0
	v_add_f32_e32 v0, 1.0, v8
	v_rcp_f32_e32 v23, v0
	v_lshl_add_u64 v[0:1], s[6:7], 0, v[100:101]
	v_and_b32_e32 v29, 0xffff0000, v12
	v_mul_f32_e32 v12, 0xbfb8aa3b, v28
	v_pk_mul_f32 v[20:21], v[22:23], v[20:21]
	v_lshlrev_b32_e32 v22, 16, v9
	v_and_b32_e32 v23, 0xffff0000, v9
	v_mul_f32_e32 v8, 0xbfb8aa3b, v22
	v_exp_f32_e32 v16, v8
	v_mul_f32_e32 v8, 0xbfb8aa3b, v23
	v_exp_f32_e32 v26, v8
	v_pk_mul_f32 v[8:9], v[20:21], v[24:25]
	v_add_f32_e32 v16, 1.0, v16
	v_rcp_f32_e32 v20, v16
	v_add_f32_e32 v16, 1.0, v26
	v_rcp_f32_e32 v21, v16
	v_cvt_pk_bf16_f32 v8, v8, v9
	v_lshlrev_b32_e32 v16, 16, v17
	v_and_b32_e32 v17, 0xffff0000, v17
	v_pk_mul_f32 v[20:21], v[20:21], v[22:23]
	v_lshlrev_b32_e32 v22, 16, v10
	v_and_b32_e32 v23, 0xffff0000, v10
	v_mul_f32_e32 v9, 0xbfb8aa3b, v22
	v_exp_f32_e32 v9, v9
	v_mul_f32_e32 v10, 0xbfb8aa3b, v23
	v_exp_f32_e32 v10, v10
	v_pk_mul_f32 v[16:17], v[20:21], v[16:17]
	v_add_f32_e32 v9, 1.0, v9
	v_rcp_f32_e32 v20, v9
	v_add_f32_e32 v9, 1.0, v10
	v_rcp_f32_e32 v21, v9
	v_add_u32_e32 v26, 16, v2
	v_cvt_pk_bf16_f32 v9, v16, v17
	v_lshlrev_b32_e32 v16, 16, v18
	v_and_b32_e32 v17, 0xffff0000, v18
	v_pk_mul_f32 v[20:21], v[20:21], v[22:23]
	v_ashrrev_i32_e32 v27, 31, v26
	v_pk_mul_f32 v[16:17], v[20:21], v[16:17]
	v_lshlrev_b32_e32 v24, 16, v11
	v_lshl_add_u64 v[20:21], s[42:43], 0, v[26:27]
	v_and_b32_e32 v25, 0xffff0000, v11
	v_mul_f32_e32 v10, 0xbfb8aa3b, v24
	v_lshlrev_b64 v[20:21], 11, v[20:21]
	v_exp_f32_e32 v11, v10
	v_mul_f32_e32 v10, 0xbfb8aa3b, v25
	v_lshl_add_u64 v[20:21], v[4:5], 0, v[20:21]
	v_exp_f32_e32 v18, v10
	v_mov_b32_e32 v20, v230
	v_mov_b32_e32 v21, v231
	v_mov_b32_e32 v22, v232
	v_mov_b32_e32 v23, v233
	v_add_f32_e32 v11, 1.0, v11
	v_cvt_pk_bf16_f32 v10, v16, v17
	v_rcp_f32_e32 v16, v11
	v_add_f32_e32 v11, 1.0, v18
	v_rcp_f32_e32 v17, v11
	v_lshlrev_b32_e32 v18, 16, v19
	v_and_b32_e32 v19, 0xffff0000, v19
	v_exp_f32_e32 v12, v12
	v_pk_mul_f32 v[16:17], v[16:17], v[24:25]
	s_nop 0
	v_pk_mul_f32 v[16:17], v[16:17], v[18:19]
	s_nop 0
	v_cvt_pk_bf16_f32 v11, v16, v17
	v_lshlrev_b64 v[16:17], 11, v[2:3]
	v_lshl_add_u64 v[24:25], v[0:1], 0, v[16:17]
	v_mul_f32_e32 v16, 0xbfb8aa3b, v29
	v_lshl_add_u32 v3, v6, 7, v32
	v_exp_f32_e32 v31, v16
	ds_read_b128 v[16:19], v3 offset:51200
	v_add_f32_e32 v3, 1.0, v12
	v_rcp_f32_e32 v30, v3
	v_add_f32_e32 v3, 1.0, v31
	v_lshlrev_b32_e32 v12, 16, v13
	v_rcp_f32_e32 v31, v3
	v_and_b32_e32 v13, 0xffff0000, v13
	v_mul_f32_e32 v3, 0xbfb8aa3b, v12
	global_store_dwordx4 v[24:25], v[8:11], off
	v_exp_f32_e32 v3, v3
	v_lshlrev_b64 v[6:7], 11, v[6:7]
	s_waitcnt lgkmcnt(0)
	v_lshlrev_b32_e32 v8, 16, v16
	v_and_b32_e32 v9, 0xffff0000, v16
	v_mul_f32_e32 v16, 0xbfb8aa3b, v13
	v_exp_f32_e32 v16, v16
	v_pk_mul_f32 v[10:11], v[30:31], v[28:29]
	v_add_f32_e32 v3, 1.0, v3
	v_pk_mul_f32 v[8:9], v[10:11], v[8:9]
	v_rcp_f32_e32 v10, v3
	v_add_f32_e32 v3, 1.0, v16
	v_rcp_f32_e32 v11, v3
	v_cvt_pk_bf16_f32 v8, v8, v9
	v_lshlrev_b32_e32 v16, 16, v17
	v_and_b32_e32 v17, 0xffff0000, v17
	v_pk_mul_f32 v[10:11], v[10:11], v[12:13]
	v_lshlrev_b32_e32 v12, 16, v14
	v_and_b32_e32 v13, 0xffff0000, v14
	v_mul_f32_e32 v3, 0xbfb8aa3b, v12
	v_exp_f32_e32 v3, v3
	v_mul_f32_e32 v9, 0xbfb8aa3b, v13
	v_exp_f32_e32 v9, v9
	v_pk_mul_f32 v[10:11], v[10:11], v[16:17]
	v_add_f32_e32 v3, 1.0, v3
	v_rcp_f32_e32 v16, v3
	v_add_f32_e32 v3, 1.0, v9
	v_rcp_f32_e32 v17, v3
	v_lshlrev_b32_e32 v14, 16, v15
	v_and_b32_e32 v15, 0xffff0000, v15
	v_mul_f32_e32 v3, 0xbfb8aa3b, v14
	v_pk_mul_f32 v[12:13], v[16:17], v[12:13]
	v_add_u32_e32 v16, 24, v2
	v_cvt_pk_bf16_f32 v9, v10, v11
	v_lshlrev_b32_e32 v10, 16, v18
	v_and_b32_e32 v11, 0xffff0000, v18
	v_exp_f32_e32 v18, v3
	v_mul_f32_e32 v3, 0xbfb8aa3b, v15
	v_ashrrev_i32_e32 v17, 31, v16
	v_exp_f32_e32 v24, v3
	v_lshl_add_u64 v[2:3], s[42:43], 0, v[16:17]
	v_lshlrev_b64 v[2:3], 11, v[2:3]
	v_lshl_add_u64 v[2:3], v[4:5], 0, v[2:3]
	v_mov_b32_e32 v2, v234
	v_mov_b32_e32 v3, v235
	v_mov_b32_e32 v4, v236
	v_mov_b32_e32 v5, v237
	v_pk_mul_f32 v[10:11], v[12:13], v[10:11]
	v_add_f32_e32 v12, 1.0, v18
	v_add_f32_e32 v13, 1.0, v24
	v_rcp_f32_e32 v12, v12
	v_rcp_f32_e32 v13, v13
	v_lshlrev_b32_e32 v18, 16, v19
	v_and_b32_e32 v19, 0xffff0000, v19
	v_cvt_pk_bf16_f32 v10, v10, v11
	v_pk_mul_f32 v[12:13], v[12:13], v[14:15]
	v_lshl_add_u64 v[6:7], v[0:1], 0, v[6:7]
	v_pk_mul_f32 v[12:13], v[12:13], v[18:19]
	s_waitcnt vmcnt(2)
	v_lshlrev_b32_e32 v18, 16, v20
	v_cvt_pk_bf16_f32 v11, v12, v13
	v_and_b32_e32 v19, 0xffff0000, v20
	v_mul_f32_e32 v13, 0xbfb8aa3b, v18
	v_exp_f32_e32 v20, v13
	v_mul_f32_e32 v13, 0xbfb8aa3b, v19
	v_exp_f32_e32 v25, v13
	v_lshl_add_u32 v12, v26, 7, v32
	v_add_f32_e32 v20, 1.0, v20
	ds_read_b128 v[12:15], v12 offset:51200
	v_rcp_f32_e32 v24, v20
	v_add_f32_e32 v20, 1.0, v25
	v_rcp_f32_e32 v25, v20
	global_store_dwordx4 v[6:7], v[8:11], off
	s_waitcnt lgkmcnt(0)
	v_lshlrev_b32_e32 v6, 16, v12
	v_and_b32_e32 v7, 0xffff0000, v12
	v_lshlrev_b32_e32 v10, 16, v21
	v_and_b32_e32 v11, 0xffff0000, v21
	v_pk_mul_f32 v[8:9], v[24:25], v[18:19]
	v_mul_f32_e32 v12, 0xbfb8aa3b, v10
	v_mul_f32_e32 v18, 0xbfb8aa3b, v11
	v_exp_f32_e32 v12, v12
	v_exp_f32_e32 v18, v18
	v_pk_mul_f32 v[6:7], v[8:9], v[6:7]
	v_add_f32_e32 v8, 1.0, v12
	v_add_f32_e32 v9, 1.0, v18
	v_rcp_f32_e32 v8, v8
	v_rcp_f32_e32 v9, v9
	v_cvt_pk_bf16_f32 v6, v6, v7
	v_lshlrev_b32_e32 v12, 16, v13
	v_and_b32_e32 v13, 0xffff0000, v13
	v_pk_mul_f32 v[8:9], v[8:9], v[10:11]
	v_lshlrev_b32_e32 v10, 16, v22
	v_and_b32_e32 v11, 0xffff0000, v22
	v_mul_f32_e32 v7, 0xbfb8aa3b, v10
	v_exp_f32_e32 v7, v7
	v_mul_f32_e32 v18, 0xbfb8aa3b, v11
	v_exp_f32_e32 v18, v18
	v_pk_mul_f32 v[8:9], v[8:9], v[12:13]
	v_add_f32_e32 v7, 1.0, v7
	v_rcp_f32_e32 v12, v7
	v_add_f32_e32 v7, 1.0, v18
	v_rcp_f32_e32 v13, v7
	v_cvt_pk_bf16_f32 v7, v8, v9
	v_lshlrev_b32_e32 v8, 16, v14
	v_and_b32_e32 v9, 0xffff0000, v14
	v_pk_mul_f32 v[10:11], v[12:13], v[10:11]
	v_lshlrev_b32_e32 v12, 16, v23
	v_and_b32_e32 v13, 0xffff0000, v23
	v_mul_f32_e32 v14, 0xbfb8aa3b, v12
	v_mul_f32_e32 v18, 0xbfb8aa3b, v13
	v_exp_f32_e32 v14, v14
	v_exp_f32_e32 v18, v18
	v_pk_mul_f32 v[8:9], v[10:11], v[8:9]
	v_add_f32_e32 v10, 1.0, v14
	v_add_f32_e32 v11, 1.0, v18
	v_rcp_f32_e32 v10, v10
	v_rcp_f32_e32 v11, v11
	v_lshlrev_b32_e32 v14, 16, v15
	v_and_b32_e32 v15, 0xffff0000, v15
	v_cvt_pk_bf16_f32 v8, v8, v9
	v_pk_mul_f32 v[10:11], v[10:11], v[12:13]
	s_waitcnt vmcnt(1)
	v_lshlrev_b32_e32 v18, 16, v2
	v_pk_mul_f32 v[10:11], v[10:11], v[14:15]
	v_and_b32_e32 v19, 0xffff0000, v2
	v_cvt_pk_bf16_f32 v9, v10, v11
	v_lshlrev_b64 v[10:11], 11, v[26:27]
	v_mul_f32_e32 v2, 0xbfb8aa3b, v18
	v_lshl_add_u64 v[14:15], v[0:1], 0, v[10:11]
	v_exp_f32_e32 v2, v2
	v_mul_f32_e32 v11, 0xbfb8aa3b, v19
	v_exp_f32_e32 v21, v11
	v_lshl_add_u32 v10, v16, 7, v32
	ds_read_b128 v[10:13], v10 offset:51200
	v_add_f32_e32 v2, 1.0, v2
	v_rcp_f32_e32 v20, v2
	v_add_f32_e32 v2, 1.0, v21
	v_rcp_f32_e32 v21, v2
	global_store_dwordx4 v[14:15], v[6:9], off
	v_lshlrev_b32_e32 v14, 16, v3
	v_and_b32_e32 v15, 0xffff0000, v3
	v_mul_f32_e32 v2, 0xbfb8aa3b, v14
	s_waitcnt lgkmcnt(0)
	v_lshlrev_b32_e32 v6, 16, v10
	v_and_b32_e32 v7, 0xffff0000, v10
	v_exp_f32_e32 v10, v2
	v_mul_f32_e32 v2, 0xbfb8aa3b, v15
	v_pk_mul_f32 v[8:9], v[20:21], v[18:19]
	v_exp_f32_e32 v18, v2
	v_pk_mul_f32 v[2:3], v[8:9], v[6:7]
	v_add_f32_e32 v6, 1.0, v10
	v_lshlrev_b32_e32 v10, 16, v4
	v_add_f32_e32 v7, 1.0, v18
	v_cvt_pk_bf16_f32 v2, v2, v3
	v_lshlrev_b32_e32 v8, 16, v11
	v_and_b32_e32 v9, 0xffff0000, v11
	v_and_b32_e32 v11, 0xffff0000, v4
	v_mul_f32_e32 v3, 0xbfb8aa3b, v10
	v_rcp_f32_e32 v6, v6
	v_rcp_f32_e32 v7, v7
	v_exp_f32_e32 v3, v3
	v_mul_f32_e32 v4, 0xbfb8aa3b, v11
	v_exp_f32_e32 v4, v4
	v_pk_mul_f32 v[6:7], v[6:7], v[14:15]
	v_add_f32_e32 v3, 1.0, v3
	v_pk_mul_f32 v[6:7], v[6:7], v[8:9]
	v_rcp_f32_e32 v8, v3
	v_add_f32_e32 v3, 1.0, v4
	v_rcp_f32_e32 v9, v3
	v_cvt_pk_bf16_f32 v3, v6, v7
	v_lshlrev_b32_e32 v6, 16, v12
	v_and_b32_e32 v7, 0xffff0000, v12
	v_pk_mul_f32 v[8:9], v[8:9], v[10:11]
	v_lshlrev_b32_e32 v10, 16, v5
	v_and_b32_e32 v11, 0xffff0000, v5
	v_mul_f32_e32 v4, 0xbfb8aa3b, v10
	v_exp_f32_e32 v12, v4
	v_mul_f32_e32 v4, 0xbfb8aa3b, v11
	v_exp_f32_e32 v14, v4
	v_pk_mul_f32 v[4:5], v[8:9], v[6:7]
	v_add_f32_e32 v6, 1.0, v12
	v_rcp_f32_e32 v6, v6
	v_add_f32_e32 v7, 1.0, v14
	v_rcp_f32_e32 v7, v7
	v_lshlrev_b32_e32 v8, 16, v13
	v_and_b32_e32 v9, 0xffff0000, v13
	v_cvt_pk_bf16_f32 v4, v4, v5
	v_pk_mul_f32 v[6:7], v[6:7], v[10:11]
	s_nop 0
	v_pk_mul_f32 v[6:7], v[6:7], v[8:9]
	s_nop 0
	v_cvt_pk_bf16_f32 v5, v6, v7
	v_lshlrev_b64 v[6:7], 11, v[16:17]
	v_lshl_add_u64 v[0:1], v[0:1], 0, v[6:7]
	global_store_dwordx4 v[0:1], v[2:5], off
	s_and_saveexec_b64 s[6:7], vcc
	s_cbranch_execz .LBB0_226
	s_movk_i32 s1, 0x200
	v_add_u32_e32 v0, s98, v64
	v_cmp_gt_u32_e32 vcc, s1, v64
	v_mov_b32_e32 v1, s46
	s_nop 0
	v_cndmask_b32_e32 v0, -2, v0, vcc
	ds_write_b32 v1, v0
	s_branch .LBB0_226
